# plus prologue w_in/w_up transposes: 16 weights + 16 gains in flight per wait instead of one element at a time
# speedup vs baseline: 1.0277x; 1.0277x over previous
; #define LAS __attribute__((address_space(3)))
; __device__ __forceinline__ void transpose_item(const float* W, int N, int k0, int n0, bf16_t* dst, int ldd, LAS float* scr, int lane, const float* gk = nullptr) {
; #pragma unroll 8
;     for (int i = 0; i < 32; ++i) { const int kk = 2 * i + (lane >> 5); scr[kk * 33 + (lane & 31)] = W[(size_t)(k0 + kk) * N + n0 + (lane & 31)] * (gk ? gk[k0 + kk] : 1.0f); }
;     asm volatile("s_waitcnt lgkmcnt(0)" ::: "memory");
; __global__ void __launch_bounds__(512, 2) fwd_mega(Args args) {
;     ...
;             if (r < I_UP) { const int kb = r / 176, nb = r % 176, n0 = 32 * nb; const int bj = n0 / DFF, ch = n0 % DFF; const int drow = (ch >> 7) * 256 + bj * 128 + (ch & 127);
;                 transpose_item(w_up + (size_t)l * DM * UPW, UPW, 64 * kb, n0, (bf16_t*)(wl + W_UP) + (size_t)drow * 1024, 1024, scr, lane, ln2 + (size_t)l * DM); continue; }
.LBB0_19:
.LBB0_20:
.Lgw1_loop:
	v_lshl_add_u64 v[96:97], v[40:41], 0, s[16:17]
	global_load_dword v128, v[96:97], off
	v_lshl_add_u64 v[98:99], v[38:39], 0, s[16:17]
	global_load_dword v129, v[98:99], off
	v_lshl_add_u64 v[100:101], v[36:37], 0, s[16:17]
	global_load_dword v130, v[100:101], off
	v_lshl_add_u64 v[102:103], v[34:35], 0, s[16:17]
	global_load_dword v131, v[102:103], off
	v_lshl_add_u64 v[104:105], v[32:33], 0, s[16:17]
	global_load_dword v132, v[104:105], off
	v_lshl_add_u64 v[106:107], v[30:31], 0, s[16:17]
	global_load_dword v133, v[106:107], off
	v_lshl_add_u64 v[108:109], v[28:29], 0, s[16:17]
	global_load_dword v134, v[108:109], off
	v_lshl_add_u64 v[110:111], v[24:25], 0, s[16:17]
	global_load_dword v135, v[110:111], off
	s_add_u32 s98, s16, 0x58000
	s_addc_u32 s99, s17, 0
	v_lshl_add_u64 v[112:113], v[40:41], 0, s[98:99]
	global_load_dword v136, v[112:113], off
	v_lshl_add_u64 v[114:115], v[38:39], 0, s[98:99]
	global_load_dword v137, v[114:115], off
	v_lshl_add_u64 v[116:117], v[36:37], 0, s[98:99]
	global_load_dword v138, v[116:117], off
	v_lshl_add_u64 v[118:119], v[34:35], 0, s[98:99]
	global_load_dword v139, v[118:119], off
	v_lshl_add_u64 v[120:121], v[32:33], 0, s[98:99]
	global_load_dword v140, v[120:121], off
	v_lshl_add_u64 v[122:123], v[30:31], 0, s[98:99]
	global_load_dword v141, v[122:123], off
	v_lshl_add_u64 v[124:125], v[28:29], 0, s[98:99]
	global_load_dword v142, v[124:125], off
	v_lshl_add_u64 v[126:127], v[24:25], 0, s[98:99]
	global_load_dword v143, v[126:127], off
	v_mov_b32_e32 v144, 1.0
	v_mov_b32_e32 v145, 1.0
	v_mov_b32_e32 v146, 1.0
	v_mov_b32_e32 v147, 1.0
	v_mov_b32_e32 v148, 1.0
	v_mov_b32_e32 v149, 1.0
	v_mov_b32_e32 v150, 1.0
	v_mov_b32_e32 v151, 1.0
	v_mov_b32_e32 v152, 1.0
	v_mov_b32_e32 v153, 1.0
	v_mov_b32_e32 v154, 1.0
	v_mov_b32_e32 v155, 1.0
	v_mov_b32_e32 v156, 1.0
	v_mov_b32_e32 v157, 1.0
	v_mov_b32_e32 v158, 1.0
	v_mov_b32_e32 v159, 1.0
	s_andn2_b64 vcc, exec, s[18:19]
	s_cbranch_vccnz .Lgw1_nog
	v_lshl_add_u64 v[160:161], s[14:15], 0, v[2:3]
	v_lshl_add_u64 v[162:163], s[14:15], 0, v[26:27]
	global_load_dword v144, v[160:161], off
	global_load_dword v152, v[160:161], off offset:64
	global_load_dword v145, v[162:163], off offset:8
	global_load_dword v153, v[162:163], off offset:72
	global_load_dword v146, v[162:163], off offset:16
	global_load_dword v154, v[162:163], off offset:80
	global_load_dword v147, v[162:163], off offset:24
	global_load_dword v155, v[162:163], off offset:88
	global_load_dword v148, v[162:163], off offset:32
	global_load_dword v156, v[162:163], off offset:96
	global_load_dword v149, v[162:163], off offset:40
	global_load_dword v157, v[162:163], off offset:104
	global_load_dword v150, v[162:163], off offset:48
	global_load_dword v158, v[162:163], off offset:112
	global_load_dword v151, v[162:163], off offset:56
	global_load_dword v159, v[162:163], off offset:120
.Lgw1_nog:
	s_waitcnt vmcnt(0)
	v_mul_f32_e32 v128, v128, v144
	ds_write_b32 v21, v128
	v_mul_f32_e32 v129, v129, v145
	ds_write_b32 v21, v129 offset:264
	v_mul_f32_e32 v130, v130, v146
	ds_write_b32 v21, v130 offset:528
	v_mul_f32_e32 v131, v131, v147
	ds_write_b32 v21, v131 offset:792
	v_mul_f32_e32 v132, v132, v148
	ds_write_b32 v21, v132 offset:1056
	v_mul_f32_e32 v133, v133, v149
	ds_write_b32 v21, v133 offset:1320
	v_mul_f32_e32 v134, v134, v150
	ds_write_b32 v21, v134 offset:1584
	v_mul_f32_e32 v135, v135, v151
	ds_write_b32 v21, v135 offset:1848
	v_mul_f32_e32 v136, v136, v152
	ds_write_b32 v21, v136 offset:2112
	v_mul_f32_e32 v137, v137, v153
	ds_write_b32 v21, v137 offset:2376
	v_mul_f32_e32 v138, v138, v154
	ds_write_b32 v21, v138 offset:2640
	v_mul_f32_e32 v139, v139, v155
	ds_write_b32 v21, v139 offset:2904
	v_mul_f32_e32 v140, v140, v156
	ds_write_b32 v21, v140 offset:3168
	v_mul_f32_e32 v141, v141, v157
	ds_write_b32 v21, v141 offset:3432
	v_mul_f32_e32 v142, v142, v158
	ds_write_b32 v21, v142 offset:3696
	v_mul_f32_e32 v143, v143, v159
	ds_write_b32 v21, v143 offset:3960
	v_add_u32_e32 v21, 0x1080, v21
	s_add_u32 s16, s16, 0xb0000
	s_addc_u32 s17, s17, 0
	s_add_u32 s14, s14, 0x80
	s_addc_u32 s15, s15, 0
	s_cmp_lg_u32 s16, 0x160000
	s_cbranch_scc1 .Lgw1_loop
	s_branch .LBB0_37

; #define LAS __attribute__((address_space(3)))
; #define ln1 (karg(6))
; #define w_in (karg(7))
; __device__ __forceinline__ void transpose_item(const float* W, int N, int k0, int n0, bf16_t* dst, int ldd, LAS float* scr, int lane, const float* gk = nullptr) {
; #pragma unroll 8
;     for (int i = 0; i < 32; ++i) { const int kk = 2 * i + (lane >> 5); scr[kk * 33 + (lane & 31)] = W[(size_t)(k0 + kk) * N + n0 + (lane & 31)] * (gk ? gk[k0 + kk] : 1.0f); }
;     asm volatile("s_waitcnt lgkmcnt(0)" ::: "memory");
; __global__ void __launch_bounds__(512, 2) fwd_mega(Args args) {
;     ...
;             if (r < I_IN) { const int kb = r / 96, nb = r % 96, n0 = 32 * nb; const int drow = n0 < 1024 ? n0 : (n0 < 1536 ? 2560 + n0 - 1024 : (n0 < 2048 ? n0 - 512 : (n0 < 2560 ? 1536 + ((n0 - 2048) >> 7) * 256 + ((n0 - 2048) & 127) : 1536 + ((n0 - 2560) >> 7) * 256 + 128 + ((n0 - 2560) & 127))));
;                 transpose_item(w_in + (size_t)l * DM * PROJ, PROJ, 64 * kb, n0, (bf16_t*)(wl + W_IN) + (size_t)drow * 1024, 1024, scr, lane, ln1 + (size_t)l * DM); continue; }
.LBB0_58:
.LBB0_59:
.Lgw2_loop:
	v_lshl_add_u64 v[96:97], v[40:41], 0, s[18:19]
	global_load_dword v128, v[96:97], off
	v_lshl_add_u64 v[98:99], v[38:39], 0, s[18:19]
	global_load_dword v129, v[98:99], off
	v_lshl_add_u64 v[100:101], v[36:37], 0, s[18:19]
	global_load_dword v130, v[100:101], off
	v_lshl_add_u64 v[102:103], v[34:35], 0, s[18:19]
	global_load_dword v131, v[102:103], off
	v_lshl_add_u64 v[104:105], v[32:33], 0, s[18:19]
	global_load_dword v132, v[104:105], off
	v_lshl_add_u64 v[106:107], v[30:31], 0, s[18:19]
	global_load_dword v133, v[106:107], off
	v_lshl_add_u64 v[108:109], v[28:29], 0, s[18:19]
	global_load_dword v134, v[108:109], off
	v_lshl_add_u64 v[110:111], v[24:25], 0, s[18:19]
	global_load_dword v135, v[110:111], off
	s_add_u32 s98, s18, 0x30000
	s_addc_u32 s99, s19, 0
	v_lshl_add_u64 v[112:113], v[40:41], 0, s[98:99]
	global_load_dword v136, v[112:113], off
	v_lshl_add_u64 v[114:115], v[38:39], 0, s[98:99]
	global_load_dword v137, v[114:115], off
	v_lshl_add_u64 v[116:117], v[36:37], 0, s[98:99]
	global_load_dword v138, v[116:117], off
	v_lshl_add_u64 v[118:119], v[34:35], 0, s[98:99]
	global_load_dword v139, v[118:119], off
	v_lshl_add_u64 v[120:121], v[32:33], 0, s[98:99]
	global_load_dword v140, v[120:121], off
	v_lshl_add_u64 v[122:123], v[30:31], 0, s[98:99]
	global_load_dword v141, v[122:123], off
	v_lshl_add_u64 v[124:125], v[28:29], 0, s[98:99]
	global_load_dword v142, v[124:125], off
	v_lshl_add_u64 v[126:127], v[24:25], 0, s[98:99]
	global_load_dword v143, v[126:127], off
	v_mov_b32_e32 v144, 1.0
	v_mov_b32_e32 v145, 1.0
	v_mov_b32_e32 v146, 1.0
	v_mov_b32_e32 v147, 1.0
	v_mov_b32_e32 v148, 1.0
	v_mov_b32_e32 v149, 1.0
	v_mov_b32_e32 v150, 1.0
	v_mov_b32_e32 v151, 1.0
	v_mov_b32_e32 v152, 1.0
	v_mov_b32_e32 v153, 1.0
	v_mov_b32_e32 v154, 1.0
	v_mov_b32_e32 v155, 1.0
	v_mov_b32_e32 v156, 1.0
	v_mov_b32_e32 v157, 1.0
	v_mov_b32_e32 v158, 1.0
	v_mov_b32_e32 v159, 1.0
	s_andn2_b64 vcc, exec, s[20:21]
	s_cbranch_vccnz .Lgw2_nog
	v_lshl_add_u64 v[160:161], s[12:13], 0, v[42:43]
	v_lshl_add_u64 v[162:163], s[12:13], 0, v[26:27]
	global_load_dword v144, v[160:161], off
	global_load_dword v152, v[160:161], off offset:64
	global_load_dword v145, v[162:163], off offset:8
	global_load_dword v153, v[162:163], off offset:72
	global_load_dword v146, v[162:163], off offset:16
	global_load_dword v154, v[162:163], off offset:80
	global_load_dword v147, v[162:163], off offset:24
	global_load_dword v155, v[162:163], off offset:88
	global_load_dword v148, v[162:163], off offset:32
	global_load_dword v156, v[162:163], off offset:96
	global_load_dword v149, v[162:163], off offset:40
	global_load_dword v157, v[162:163], off offset:104
	global_load_dword v150, v[162:163], off offset:48
	global_load_dword v158, v[162:163], off offset:112
	global_load_dword v151, v[162:163], off offset:56
	global_load_dword v159, v[162:163], off offset:120
.Lgw2_nog:
	s_waitcnt vmcnt(0)
	v_mul_f32_e32 v128, v128, v144
	ds_write_b32 v2, v128
	v_mul_f32_e32 v129, v129, v145
	ds_write_b32 v2, v129 offset:264
	v_mul_f32_e32 v130, v130, v146
	ds_write_b32 v2, v130 offset:528
	v_mul_f32_e32 v131, v131, v147
	ds_write_b32 v2, v131 offset:792
	v_mul_f32_e32 v132, v132, v148
	ds_write_b32 v2, v132 offset:1056
	v_mul_f32_e32 v133, v133, v149
	ds_write_b32 v2, v133 offset:1320
	v_mul_f32_e32 v134, v134, v150
	ds_write_b32 v2, v134 offset:1584
	v_mul_f32_e32 v135, v135, v151
	ds_write_b32 v2, v135 offset:1848
	v_mul_f32_e32 v136, v136, v152
	ds_write_b32 v2, v136 offset:2112
	v_mul_f32_e32 v137, v137, v153
	ds_write_b32 v2, v137 offset:2376
	v_mul_f32_e32 v138, v138, v154
	ds_write_b32 v2, v138 offset:2640
	v_mul_f32_e32 v139, v139, v155
	ds_write_b32 v2, v139 offset:2904
	v_mul_f32_e32 v140, v140, v156
	ds_write_b32 v2, v140 offset:3168
	v_mul_f32_e32 v141, v141, v157
	ds_write_b32 v2, v141 offset:3432
	v_mul_f32_e32 v142, v142, v158
	ds_write_b32 v2, v142 offset:3696
	v_mul_f32_e32 v143, v143, v159
	ds_write_b32 v2, v143 offset:3960
	v_add_u32_e32 v2, 0x1080, v2
	s_add_u32 s18, s18, 0x60000
	s_addc_u32 s19, s19, 0
	s_add_u32 s12, s12, 0x80
	s_addc_u32 s13, s13, 0
	s_cmp_lg_u32 s18, 0xc0000
	s_cbranch_scc1 .Lgw2_loop
	s_branch .LBB0_9
